# GEMM epilogues: epilogue loads issued before the leading half's align barrier (barrier moved down to the vmcnt(0) that consumes them)
# speedup vs baseline: 1.0131x; 1.0024x over previous
.LBB0_261:
	s_cmp_eq_u32 s46, s99
	s_cbranch_scc1 .Lp2_rr_hit
	v_lshl_add_u32 v178, s46, 8, v181
	v_ashrrev_i32_e32 v179, 31, v178
	v_lshlrev_b64 v[128:129], 6, v[178:179]
	v_or_b32_e32 v176, 16, v178
	v_lshl_add_u64 v[128:129], v[158:159], 0, v[128:129]
	v_ashrrev_i32_e32 v177, 31, v176
	global_load_dwordx4 v[202:205], v[128:129], off
	v_lshlrev_b64 v[128:129], 6, v[176:177]
	v_lshl_add_u64 v[128:129], v[158:159], 0, v[128:129]
	global_load_dwordx4 v[206:209], v[128:129], off
	v_or_b32_e32 v174, 32, v178
	v_ashrrev_i32_e32 v175, 31, v174
	v_lshlrev_b64 v[128:129], 6, v[174:175]
	v_or_b32_e32 v172, 48, v178
	v_lshl_add_u64 v[128:129], v[158:159], 0, v[128:129]
	v_ashrrev_i32_e32 v173, 31, v172
	global_load_dwordx4 v[148:151], v[128:129], off
	v_lshlrev_b64 v[128:129], 6, v[172:173]
	v_lshl_add_u64 v[128:129], v[158:159], 0, v[128:129]
	global_load_dwordx4 v[144:147], v[128:129], off
	v_add_u32_e32 v170, 0x80, v178
	v_ashrrev_i32_e32 v171, 31, v170
	v_lshlrev_b64 v[128:129], 6, v[170:171]
	v_add_u32_e32 v168, 0x90, v178
	v_lshl_add_u64 v[128:129], v[158:159], 0, v[128:129]
	v_ashrrev_i32_e32 v169, 31, v168
	global_load_dwordx4 v[140:143], v[128:129], off
	v_lshlrev_b64 v[128:129], 6, v[168:169]
	v_lshl_add_u64 v[128:129], v[158:159], 0, v[128:129]
	global_load_dwordx4 v[136:139], v[128:129], off
	v_add_u32_e32 v166, 0xa0, v178
	v_ashrrev_i32_e32 v167, 31, v166
	v_lshlrev_b64 v[128:129], 6, v[166:167]
	v_add_u32_e32 v164, 0xb0, v178
	v_lshl_add_u64 v[128:129], v[158:159], 0, v[128:129]
	v_ashrrev_i32_e32 v165, 31, v164
	global_load_dwordx4 v[132:135], v[128:129], off
	v_lshlrev_b64 v[128:129], 6, v[164:165]
	v_lshl_add_u64 v[128:129], v[158:159], 0, v[128:129]
	global_load_dwordx4 v[128:131], v[128:129], off
	v_and_b32_e32 v182, 64, v239
	v_xor_b32_e32 v180, 16, v239
	v_add_u32_e32 v182, 64, v182
	v_cmp_lt_i32_e32 vcc, v180, v182
	s_and_b64 s[100:101], exec, s[26:27]
	s_cbranch_scc0 .Lal261m
	s_barrier
.Lal261m:
	s_cmp_gt_i32 s86, 13
	s_waitcnt vmcnt(0)
	v_add_f32_e32 v247, v202, v203
	v_add_f32_e32 v248, v204, v205
	v_add_f32_e32 v230, v247, v248
	v_add_f32_e32 v249, v206, v207
	v_add_f32_e32 v250, v208, v209
	v_add_f32_e32 v231, v249, v250
	v_add_f32_e32 v247, v148, v149
	v_add_f32_e32 v248, v150, v151
	v_add_f32_e32 v232, v247, v248
	v_add_f32_e32 v249, v144, v145
	v_add_f32_e32 v250, v146, v147
	v_add_f32_e32 v233, v249, v250
	v_add_f32_e32 v247, v140, v141
	v_add_f32_e32 v248, v142, v143
	v_add_f32_e32 v234, v247, v248
	v_add_f32_e32 v249, v136, v137
	v_add_f32_e32 v250, v138, v139
	v_add_f32_e32 v235, v249, v250
	v_add_f32_e32 v247, v132, v133
	v_add_f32_e32 v248, v134, v135
	v_add_f32_e32 v242, v247, v248
	v_add_f32_e32 v249, v128, v129
	v_add_f32_e32 v250, v130, v131
	v_add_f32_e32 v243, v249, v250
	s_mov_b32 s99, s46
	s_branch .Lp2_rr_join
.Lp2_rr_hit:
	s_and_b64 s[100:101], exec, s[26:27]
	s_cbranch_scc0 .Lal261h
	s_barrier

.LBB0_862:
	v_lshl_or_b32 v212, s57, 8, v249
	v_lshl_add_u32 v214, s60, 8, v247
	v_ashrrev_i32_e32 v213, 31, v212
	v_lshlrev_b64 v[232:233], 1, v[212:213]
	v_ashrrev_i32_e32 v215, 31, v214
	v_lshl_add_u64 v[88:89], s[12:13], 0, v[232:233]
	v_lshlrev_b64 v[234:235], 11, v[214:215]
	v_lshl_add_u64 v[90:91], v[88:89], 0, v[234:235]
	global_load_dwordx4 v[188:191], v[90:91], off
	global_load_dwordx4 v[184:187], v[90:91], off offset:256
	v_or_b32_e32 v228, 16, v214
	v_ashrrev_i32_e32 v229, 31, v228
	v_or_b32_e32 v224, 32, v214
	v_lshlrev_b64 v[230:231], 11, v[228:229]
	v_ashrrev_i32_e32 v225, 31, v224
	v_or_b32_e32 v220, 48, v214
	v_lshl_add_u64 v[90:91], v[88:89], 0, v[230:231]
	v_lshlrev_b64 v[226:227], 11, v[224:225]
	v_ashrrev_i32_e32 v221, 31, v220
	v_add_u32_e32 v216, 0x80, v214
	global_load_dwordx4 v[180:183], v[90:91], off
	global_load_dwordx4 v[176:179], v[90:91], off offset:256
	v_lshl_add_u64 v[90:91], v[88:89], 0, v[226:227]
	v_lshlrev_b64 v[222:223], 11, v[220:221]
	v_ashrrev_i32_e32 v217, 31, v216
	global_load_dwordx4 v[172:175], v[90:91], off
	global_load_dwordx4 v[168:171], v[90:91], off offset:256
	v_lshl_add_u64 v[90:91], v[88:89], 0, v[222:223]
	v_lshlrev_b64 v[218:219], 11, v[216:217]
	global_load_dwordx4 v[164:167], v[90:91], off
	global_load_dwordx4 v[160:163], v[90:91], off offset:256
	v_lshl_add_u64 v[90:91], v[88:89], 0, v[218:219]
	global_load_dwordx4 v[156:159], v[90:91], off
	global_load_dwordx4 v[148:151], v[90:91], off offset:256
	v_add_u32_e32 v90, 0x90, v214
	v_ashrrev_i32_e32 v91, 31, v90
	v_lshlrev_b64 v[90:91], 11, v[90:91]
	v_lshl_add_u64 v[90:91], v[88:89], 0, v[90:91]
	global_load_dwordx4 v[140:143], v[90:91], off
	global_load_dwordx4 v[136:139], v[90:91], off offset:256
	v_add_u32_e32 v90, 0xa0, v214
	v_ashrrev_i32_e32 v91, 31, v90
	v_lshlrev_b64 v[90:91], 11, v[90:91]
	v_lshl_add_u64 v[90:91], v[88:89], 0, v[90:91]
	global_load_dwordx4 v[124:127], v[90:91], off
	global_load_dwordx4 v[112:115], v[90:91], off offset:256
	v_add_u32_e32 v90, 0xb0, v214
	v_ashrrev_i32_e32 v91, 31, v90
	v_lshlrev_b64 v[90:91], 11, v[90:91]
	v_lshl_add_u64 v[88:89], v[88:89], 0, v[90:91]
	global_load_dwordx4 v[100:103], v[88:89], off
	s_nop 0
	global_load_dwordx4 v[88:91], v[88:89], off offset:256
	v_and_b32_e32 v243, 64, v239
	v_xor_b32_e32 v242, 16, v239
	v_add_u32_e32 v243, 64, v243
	v_cmp_lt_i32_e32 vcc, v242, v243
	s_lshl_b32 s28, s57, 2
	s_ashr_i32 s29, s28, 31
	v_cndmask_b32_e32 v242, v239, v242, vcc
	v_lshlrev_b32_e32 v251, 2, v242
	v_xor_b32_e32 v242, 32, v239
	v_cmp_lt_i32_e32 vcc, v242, v243
	s_and_b64 s[100:101], exec, s[18:19]
	s_cbranch_scc0 .Lal862m
	s_barrier
.Lal862m:
	s_waitcnt vmcnt(0)
	v_and_b32_e32 v243, 0xffff0000, v188
	v_cndmask_b32_e32 v242, v239, v242, vcc
	v_lshlrev_b32_e32 v252, 2, v242
	v_lshlrev_b32_e32 v242, 16, v188
	v_lshlrev_b32_e32 v188, 16, v189
	v_and_b32_e32 v189, 0xffff0000, v189
	v_pk_add_f32 v[152:153], v[152:153], v[242:243]
	v_pk_add_f32 v[154:155], v[154:155], v[188:189]
	v_cvt_pk_bf16_f32 v152, v152, v153
	v_cvt_pk_bf16_f32 v153, v154, v155
	v_lshlrev_b32_e32 v154, 16, v190
	v_and_b32_e32 v155, 0xffff0000, v190
	v_pk_add_f32 v[144:145], v[144:145], v[154:155]
	s_nop 0
	v_cvt_pk_bf16_f32 v154, v144, v145
	v_lshlrev_b32_e32 v144, 16, v191
	v_and_b32_e32 v145, 0xffff0000, v191
	v_pk_add_f32 v[144:145], v[146:147], v[144:145]
	v_and_b32_e32 v147, 0xffff0000, v152
	v_cvt_pk_bf16_f32 v155, v144, v145
	v_lshl_add_u64 v[144:145], s[12:13], 0, v[234:235]
	v_lshl_add_u64 v[144:145], v[144:145], 0, v[232:233]
	global_store_dwordx4 v[144:145], v[152:155], off
	v_lshlrev_b32_e32 v146, 16, v152
	v_mul_f32_e32 v147, v147, v147
	v_lshlrev_b32_e32 v152, 16, v153
	v_and_b32_e32 v153, 0xffff0000, v153
	v_fmac_f32_e32 v147, v146, v146
	v_mul_f32_e32 v146, v153, v153
	v_lshlrev_b32_e32 v188, 16, v154
	v_and_b32_e32 v154, 0xffff0000, v154
	v_lshlrev_b32_e32 v189, 16, v155
	v_and_b32_e32 v155, 0xffff0000, v155
	v_fmac_f32_e32 v146, v152, v152
	v_add_f32_e32 v146, v147, v146
	v_mul_f32_e32 v147, v154, v154
	v_mul_f32_e32 v152, v155, v155
	v_fmac_f32_e32 v147, v188, v188
	v_fmac_f32_e32 v152, v189, v189
	v_add_f32_e32 v147, v147, v152
	v_add_f32_e32 v152, v146, v147
	v_lshlrev_b32_e32 v146, 16, v184
	v_and_b32_e32 v147, 0xffff0000, v184
	v_pk_add_f32 v[132:133], v[132:133], v[146:147]
	v_lshlrev_b32_e32 v146, 16, v185
	v_and_b32_e32 v147, 0xffff0000, v185
	v_pk_add_f32 v[134:135], v[134:135], v[146:147]
	v_cvt_pk_bf16_f32 v132, v132, v133
	v_cvt_pk_bf16_f32 v133, v134, v135
	v_lshlrev_b32_e32 v134, 16, v186
	v_and_b32_e32 v135, 0xffff0000, v186
	v_pk_add_f32 v[128:129], v[128:129], v[134:135]
	s_nop 0
	v_cvt_pk_bf16_f32 v134, v128, v129
	v_lshlrev_b32_e32 v128, 16, v187
	v_and_b32_e32 v129, 0xffff0000, v187
	v_pk_add_f32 v[128:129], v[130:131], v[128:129]
	v_and_b32_e32 v131, 0xffff0000, v133
	v_cvt_pk_bf16_f32 v135, v128, v129
	v_and_b32_e32 v129, 0xffff0000, v132
	v_lshlrev_b32_e32 v128, 16, v132
	v_mul_f32_e32 v129, v129, v129
	v_lshlrev_b32_e32 v130, 16, v133
	v_fmac_f32_e32 v129, v128, v128
	v_mul_f32_e32 v128, v131, v131
	global_store_dwordx4 v[144:145], v[132:135], off offset:256
	v_fmac_f32_e32 v128, v130, v130
	v_add_f32_e32 v128, v129, v128
	v_lshlrev_b32_e32 v132, 16, v134
	v_and_b32_e32 v133, 0xffff0000, v134
	v_lshlrev_b32_e32 v134, 16, v135
	v_and_b32_e32 v135, 0xffff0000, v135
	v_mul_f32_e32 v129, v133, v133
	v_mul_f32_e32 v130, v135, v135
	v_fmac_f32_e32 v129, v132, v132
	v_fmac_f32_e32 v130, v134, v134
	v_add_f32_e32 v129, v129, v130
	v_add_f32_e32 v128, v128, v129
	v_add_f32_e32 v128, v152, v128
	ds_bpermute_b32 v129, v251, v128
	s_waitcnt lgkmcnt(0)
	v_add_f32_e32 v128, v128, v129
	ds_bpermute_b32 v129, v252, v128
	s_and_saveexec_b64 s[30:31], s[6:7]
	s_movk_i32 s82, 0x180
	s_cbranch_execz .LBB0_864
	s_waitcnt lgkmcnt(0)
	v_add_f32_e32 v130, v128, v129
	v_lshlrev_b64 v[128:129], 6, v[214:215]
	v_lshl_add_u64 v[128:129], s[14:15], 0, v[128:129]
	v_lshl_add_u64 v[128:129], s[28:29], 2, v[128:129]
	s_lshl_b32 s68, s51, 2
	v_lshl_add_u64 v[128:129], v[128:129], 0, s[68:69]
	global_store_dword v[128:129], v130, off

.LBB0_938:
	s_cmp_eq_u32 s51, s99
	s_cbranch_scc1 .Lp8_rr_hit
	v_lshl_add_u32 v178, s51, 8, v183
	v_ashrrev_i32_e32 v179, 31, v178
	v_lshlrev_b64 v[128:129], 6, v[178:179]
	v_or_b32_e32 v176, 16, v178
	v_lshl_add_u64 v[128:129], v[158:159], 0, v[128:129]
	v_ashrrev_i32_e32 v177, 31, v176
	global_load_dwordx4 v[202:205], v[128:129], off
	v_lshlrev_b64 v[128:129], 6, v[176:177]
	v_lshl_add_u64 v[128:129], v[158:159], 0, v[128:129]
	global_load_dwordx4 v[206:209], v[128:129], off
	v_or_b32_e32 v174, 32, v178
	v_ashrrev_i32_e32 v175, 31, v174
	v_lshlrev_b64 v[128:129], 6, v[174:175]
	v_or_b32_e32 v172, 48, v178
	v_lshl_add_u64 v[128:129], v[158:159], 0, v[128:129]
	v_ashrrev_i32_e32 v173, 31, v172
	global_load_dwordx4 v[148:151], v[128:129], off
	v_lshlrev_b64 v[128:129], 6, v[172:173]
	v_lshl_add_u64 v[128:129], v[158:159], 0, v[128:129]
	global_load_dwordx4 v[144:147], v[128:129], off
	v_add_u32_e32 v170, 0x80, v178
	v_ashrrev_i32_e32 v171, 31, v170
	v_lshlrev_b64 v[128:129], 6, v[170:171]
	v_add_u32_e32 v168, 0x90, v178
	v_lshl_add_u64 v[128:129], v[158:159], 0, v[128:129]
	v_ashrrev_i32_e32 v169, 31, v168
	global_load_dwordx4 v[140:143], v[128:129], off
	v_lshlrev_b64 v[128:129], 6, v[168:169]
	v_lshl_add_u64 v[128:129], v[158:159], 0, v[128:129]
	global_load_dwordx4 v[136:139], v[128:129], off
	v_add_u32_e32 v166, 0xa0, v178
	v_ashrrev_i32_e32 v167, 31, v166
	v_lshlrev_b64 v[128:129], 6, v[166:167]
	v_add_u32_e32 v164, 0xb0, v178
	v_lshl_add_u64 v[128:129], v[158:159], 0, v[128:129]
	v_ashrrev_i32_e32 v165, 31, v164
	global_load_dwordx4 v[132:135], v[128:129], off
	v_lshlrev_b64 v[128:129], 6, v[164:165]
	v_lshl_add_u64 v[128:129], v[158:159], 0, v[128:129]
	global_load_dwordx4 v[128:131], v[128:129], off
	v_and_b32_e32 v167, 64, v239
	v_xor_b32_e32 v165, 16, v239
	v_add_u32_e32 v169, 64, v167
	v_cmp_lt_i32_e32 vcc, v165, v169
	v_lshl_or_b32 v180, s50, 7, v188
	v_ashrrev_i32_e32 v181, 31, v180
	v_cndmask_b32_e32 v165, v239, v165, vcc
	v_lshlrev_b32_e32 v167, 2, v165
	v_xor_b32_e32 v165, 32, v239
	v_cmp_lt_i32_e32 vcc, v165, v169
	s_movk_i32 s82, 0x180
	s_and_b64 s[100:101], exec, s[14:15]
	s_cbranch_scc0 .Lal938m
	s_barrier
.Lal938m:
	s_waitcnt vmcnt(0)
	v_add_f32_e32 v247, v202, v203
	v_add_f32_e32 v248, v204, v205
	v_add_f32_e32 v230, v247, v248
	v_add_f32_e32 v249, v206, v207
	v_add_f32_e32 v250, v208, v209
	v_add_f32_e32 v231, v249, v250
	v_add_f32_e32 v247, v148, v149
	v_add_f32_e32 v248, v150, v151
	v_add_f32_e32 v232, v247, v248
	v_add_f32_e32 v249, v144, v145
	v_add_f32_e32 v250, v146, v147
	v_add_f32_e32 v233, v249, v250
	v_add_f32_e32 v247, v140, v141
	v_add_f32_e32 v248, v142, v143
	v_add_f32_e32 v234, v247, v248
	v_add_f32_e32 v249, v136, v137
	v_add_f32_e32 v250, v138, v139
	v_add_f32_e32 v235, v249, v250
	v_add_f32_e32 v247, v132, v133
	v_add_f32_e32 v248, v134, v135
	v_add_f32_e32 v242, v247, v248
	v_add_f32_e32 v249, v128, v129
	v_add_f32_e32 v250, v130, v131
	v_add_f32_e32 v243, v249, v250
	s_mov_b32 s99, s51
	s_branch .Lp8_rr_join
.Lp8_rr_hit:
	s_and_b64 s[100:101], exec, s[14:15]
	s_cbranch_scc0 .Lal938h
	s_barrier

.LBB0_1007:
	v_lshl_or_b32 v212, s54, 8, v249
	v_lshl_add_u32 v214, s55, 8, v247
	v_ashrrev_i32_e32 v213, 31, v212
	v_lshlrev_b64 v[232:233], 1, v[212:213]
	v_ashrrev_i32_e32 v215, 31, v214
	v_lshl_add_u64 v[88:89], s[12:13], 0, v[232:233]
	v_lshlrev_b64 v[234:235], 11, v[214:215]
	v_lshl_add_u64 v[90:91], v[88:89], 0, v[234:235]
	global_load_dwordx4 v[188:191], v[90:91], off
	global_load_dwordx4 v[184:187], v[90:91], off offset:256
	v_or_b32_e32 v228, 16, v214
	v_ashrrev_i32_e32 v229, 31, v228
	v_or_b32_e32 v224, 32, v214
	v_lshlrev_b64 v[230:231], 11, v[228:229]
	v_ashrrev_i32_e32 v225, 31, v224
	v_or_b32_e32 v220, 48, v214
	v_lshl_add_u64 v[90:91], v[88:89], 0, v[230:231]
	v_lshlrev_b64 v[226:227], 11, v[224:225]
	v_ashrrev_i32_e32 v221, 31, v220
	v_add_u32_e32 v216, 0x80, v214
	global_load_dwordx4 v[180:183], v[90:91], off
	global_load_dwordx4 v[176:179], v[90:91], off offset:256
	v_lshl_add_u64 v[90:91], v[88:89], 0, v[226:227]
	v_lshlrev_b64 v[222:223], 11, v[220:221]
	v_ashrrev_i32_e32 v217, 31, v216
	global_load_dwordx4 v[172:175], v[90:91], off
	global_load_dwordx4 v[168:171], v[90:91], off offset:256
	v_lshl_add_u64 v[90:91], v[88:89], 0, v[222:223]
	v_lshlrev_b64 v[218:219], 11, v[216:217]
	global_load_dwordx4 v[164:167], v[90:91], off
	global_load_dwordx4 v[160:163], v[90:91], off offset:256
	v_lshl_add_u64 v[90:91], v[88:89], 0, v[218:219]
	global_load_dwordx4 v[156:159], v[90:91], off
	global_load_dwordx4 v[148:151], v[90:91], off offset:256
	v_add_u32_e32 v90, 0x90, v214
	v_ashrrev_i32_e32 v91, 31, v90
	v_lshlrev_b64 v[90:91], 11, v[90:91]
	v_lshl_add_u64 v[90:91], v[88:89], 0, v[90:91]
	global_load_dwordx4 v[140:143], v[90:91], off
	global_load_dwordx4 v[136:139], v[90:91], off offset:256
	v_add_u32_e32 v90, 0xa0, v214
	v_ashrrev_i32_e32 v91, 31, v90
	v_lshlrev_b64 v[90:91], 11, v[90:91]
	v_lshl_add_u64 v[90:91], v[88:89], 0, v[90:91]
	global_load_dwordx4 v[124:127], v[90:91], off
	global_load_dwordx4 v[112:115], v[90:91], off offset:256
	v_add_u32_e32 v90, 0xb0, v214
	v_ashrrev_i32_e32 v91, 31, v90
	v_lshlrev_b64 v[90:91], 11, v[90:91]
	v_lshl_add_u64 v[88:89], v[88:89], 0, v[90:91]
	global_load_dwordx4 v[100:103], v[88:89], off
	s_nop 0
	global_load_dwordx4 v[88:91], v[88:89], off offset:256
	v_and_b32_e32 v243, 64, v239
	v_xor_b32_e32 v242, 16, v239
	v_add_u32_e32 v243, 64, v243
	v_cmp_lt_i32_e32 vcc, v242, v243
	s_lshl_b32 s22, s54, 2
	s_ashr_i32 s23, s22, 31
	v_cndmask_b32_e32 v242, v239, v242, vcc
	v_lshlrev_b32_e32 v251, 2, v242
	v_xor_b32_e32 v242, 32, v239
	v_cmp_lt_i32_e32 vcc, v242, v243
	s_and_b64 s[100:101], exec, s[18:19]
	s_cbranch_scc0 .Lal1007m
	s_barrier
.Lal1007m:
	s_waitcnt vmcnt(0)
	v_and_b32_e32 v243, 0xffff0000, v188
	v_cndmask_b32_e32 v242, v239, v242, vcc
	v_lshlrev_b32_e32 v252, 2, v242
	v_lshlrev_b32_e32 v242, 16, v188
	v_lshlrev_b32_e32 v188, 16, v189
	v_and_b32_e32 v189, 0xffff0000, v189
	v_pk_add_f32 v[152:153], v[152:153], v[242:243]
	v_pk_add_f32 v[154:155], v[154:155], v[188:189]
	v_cvt_pk_bf16_f32 v152, v152, v153
	v_cvt_pk_bf16_f32 v153, v154, v155
	v_lshlrev_b32_e32 v154, 16, v190
	v_and_b32_e32 v155, 0xffff0000, v190
	v_pk_add_f32 v[144:145], v[144:145], v[154:155]
	s_nop 0
	v_cvt_pk_bf16_f32 v154, v144, v145
	v_lshlrev_b32_e32 v144, 16, v191
	v_and_b32_e32 v145, 0xffff0000, v191
	v_pk_add_f32 v[144:145], v[146:147], v[144:145]
	v_and_b32_e32 v147, 0xffff0000, v152
	v_cvt_pk_bf16_f32 v155, v144, v145
	v_lshl_add_u64 v[144:145], s[12:13], 0, v[234:235]
	v_lshl_add_u64 v[144:145], v[144:145], 0, v[232:233]
	global_store_dwordx4 v[144:145], v[152:155], off
	v_lshlrev_b32_e32 v146, 16, v152
	v_mul_f32_e32 v147, v147, v147
	v_lshlrev_b32_e32 v152, 16, v153
	v_and_b32_e32 v153, 0xffff0000, v153
	v_fmac_f32_e32 v147, v146, v146
	v_mul_f32_e32 v146, v153, v153
	v_lshlrev_b32_e32 v188, 16, v154
	v_and_b32_e32 v154, 0xffff0000, v154
	v_lshlrev_b32_e32 v189, 16, v155
	v_and_b32_e32 v155, 0xffff0000, v155
	v_fmac_f32_e32 v146, v152, v152
	v_add_f32_e32 v146, v147, v146
	v_mul_f32_e32 v147, v154, v154
	v_mul_f32_e32 v152, v155, v155
	v_fmac_f32_e32 v147, v188, v188
	v_fmac_f32_e32 v152, v189, v189
	v_add_f32_e32 v147, v147, v152
	v_add_f32_e32 v152, v146, v147
	v_lshlrev_b32_e32 v146, 16, v184
	v_and_b32_e32 v147, 0xffff0000, v184
	v_pk_add_f32 v[132:133], v[132:133], v[146:147]
	v_lshlrev_b32_e32 v146, 16, v185
	v_and_b32_e32 v147, 0xffff0000, v185
	v_pk_add_f32 v[134:135], v[134:135], v[146:147]
	v_cvt_pk_bf16_f32 v132, v132, v133
	v_cvt_pk_bf16_f32 v133, v134, v135
	v_lshlrev_b32_e32 v134, 16, v186
	v_and_b32_e32 v135, 0xffff0000, v186
	v_pk_add_f32 v[128:129], v[128:129], v[134:135]
	s_nop 0
	v_cvt_pk_bf16_f32 v134, v128, v129
	v_lshlrev_b32_e32 v128, 16, v187
	v_and_b32_e32 v129, 0xffff0000, v187
	v_pk_add_f32 v[128:129], v[130:131], v[128:129]
	v_and_b32_e32 v131, 0xffff0000, v133
	v_cvt_pk_bf16_f32 v135, v128, v129
	v_and_b32_e32 v129, 0xffff0000, v132
	v_lshlrev_b32_e32 v128, 16, v132
	v_mul_f32_e32 v129, v129, v129
	v_lshlrev_b32_e32 v130, 16, v133
	v_fmac_f32_e32 v129, v128, v128
	v_mul_f32_e32 v128, v131, v131
	global_store_dwordx4 v[144:145], v[132:135], off offset:256
	v_fmac_f32_e32 v128, v130, v130
	v_add_f32_e32 v128, v129, v128
	v_lshlrev_b32_e32 v132, 16, v134
	v_and_b32_e32 v133, 0xffff0000, v134
	v_lshlrev_b32_e32 v134, 16, v135
	v_and_b32_e32 v135, 0xffff0000, v135
	v_mul_f32_e32 v129, v133, v133
	v_mul_f32_e32 v130, v135, v135
	v_fmac_f32_e32 v129, v132, v132
	v_fmac_f32_e32 v130, v134, v134
	v_add_f32_e32 v129, v129, v130
	v_add_f32_e32 v128, v128, v129
	v_add_f32_e32 v128, v152, v128
	ds_bpermute_b32 v129, v251, v128
	s_waitcnt lgkmcnt(0)
	v_add_f32_e32 v128, v128, v129
	ds_bpermute_b32 v129, v252, v128
	s_and_saveexec_b64 s[24:25], s[4:5]
	s_cbranch_execz .LBB0_1009
	s_waitcnt lgkmcnt(0)
	v_add_f32_e32 v130, v128, v129
	v_lshlrev_b64 v[128:129], 6, v[214:215]
	v_lshl_add_u64 v[128:129], s[14:15], 0, v[128:129]
	v_lshl_add_u64 v[128:129], s[22:23], 2, v[128:129]
	s_lshl_b32 s68, s46, 2
	v_lshl_add_u64 v[128:129], v[128:129], 0, s[68:69]
	global_store_dword v[128:129], v130, off
